# v7 + final RMSNorm (P16): gain-vector loads hoisted out of the store ladder, per-store vmcnt(0) removed
# baseline (speedup 1.0000x reference)
.LBB0_1450:
	global_load_dwordx4 v[152:155], v[16:17], off offset:16
	global_load_dwordx4 v[156:159], v[16:17], off offset:2048
	global_load_dwordx4 v[160:163], v[16:17], off offset:2064
	global_load_dwordx4 v[164:167], v[18:19], off
	global_load_dwordx4 v[168:171], v[20:21], off
	global_load_dwordx4 v[172:175], v[22:23], off
	global_load_dwordx4 v[176:179], v[24:25], off
	global_load_dwordx4 v[180:183], v[26:27], off
	global_load_dwordx4 v[184:187], v[28:29], off
	global_load_dwordx4 v[188:191], v[30:31], off
	global_load_dwordx4 v[192:195], v[32:33], off
	global_load_dwordx4 v[196:199], v[34:35], off
	global_load_dwordx4 v[200:203], v[36:37], off
	global_load_dwordx4 v[204:207], v[38:39], off
	global_load_dwordx4 v[208:211], v[40:41], off
	global_load_dwordx4 v[0:3], v[44:45], off
	global_load_dwordx4 v[4:7], v[44:45], off offset:1024
	global_load_dwordx4 v[8:11], v[44:45], off offset:2048
	global_load_dwordx4 v[12:15], v[44:45], off offset:3072
	v_add_co_u32_e32 v50, vcc, s6, v44
	s_add_i32 s90, s90, s92
	s_nop 0
	v_addc_co_u32_e32 v51, vcc, 0, v45, vcc
	global_load_dwordx4 v[88:91], v[16:17], off
	global_load_dwordx4 v[46:49], v[50:51], off
	global_load_dwordx4 v[92:95], v[50:51], off offset:1024
	global_load_dwordx4 v[96:99], v[50:51], off offset:2048
	global_load_dwordx4 v[100:103], v[50:51], off offset:3072
	v_lshl_add_u64 v[44:45], v[44:45], 0, s[4:5]
	s_cmpk_lt_i32 s90, 0x2000
	s_waitcnt vmcnt(8)
	v_and_b32_e32 v107, 0xffff0000, v1
	v_and_b32_e32 v106, 0xffff0000, v0
	v_and_b32_e32 v111, 0xffff0000, v3
	v_and_b32_e32 v110, 0xffff0000, v2
	s_waitcnt vmcnt(7)
	v_and_b32_e32 v115, 0xffff0000, v5
	v_and_b32_e32 v114, 0xffff0000, v4
	v_and_b32_e32 v119, 0xffff0000, v7
	v_and_b32_e32 v118, 0xffff0000, v6
	v_lshlrev_b32_e32 v105, 16, v1
	v_lshlrev_b32_e32 v104, 16, v0
	v_lshlrev_b32_e32 v109, 16, v3
	v_lshlrev_b32_e32 v108, 16, v2
	v_lshlrev_b32_e32 v113, 16, v5
	v_lshlrev_b32_e32 v112, 16, v4
	v_lshlrev_b32_e32 v117, 16, v7
	v_lshlrev_b32_e32 v116, 16, v6
	s_waitcnt vmcnt(6)
	v_and_b32_e32 v77, 0xffff0000, v8
	v_and_b32_e32 v79, 0xffff0000, v9
	v_and_b32_e32 v73, 0xffff0000, v10
	v_and_b32_e32 v75, 0xffff0000, v11
	s_waitcnt vmcnt(5)
	v_lshlrev_b32_e32 v64, 16, v14
	v_pk_mul_f32 v[120:121], v[106:107], v[106:107]
	v_pk_mul_f32 v[122:123], v[110:111], v[110:111]
	v_pk_mul_f32 v[124:125], v[114:115], v[114:115]
	v_pk_mul_f32 v[126:127], v[118:119], v[118:119]
	v_lshlrev_b32_e32 v76, 16, v8
	v_lshlrev_b32_e32 v78, 16, v9
	v_lshlrev_b32_e32 v72, 16, v10
	v_lshlrev_b32_e32 v74, 16, v11
	v_lshlrev_b32_e32 v68, 16, v12
	v_and_b32_e32 v69, 0xffff0000, v12
	v_lshlrev_b32_e32 v70, 16, v13
	v_and_b32_e32 v71, 0xffff0000, v13
	v_and_b32_e32 v65, 0xffff0000, v14
	v_lshlrev_b32_e32 v66, 16, v15
	v_and_b32_e32 v67, 0xffff0000, v15
	v_mul_f32_e32 v133, v64, v64
	v_mul_f32_e32 v62, v77, v77
	v_mul_f32_e32 v128, v79, v79
	v_mul_f32_e32 v130, v73, v73
	v_mul_f32_e32 v132, v75, v75
	s_waitcnt vmcnt(3)
	v_lshlrev_b32_e32 v57, 16, v48
	v_lshlrev_b32_e32 v56, 16, v46
	v_and_b32_e32 v55, 0xffff0000, v48
	v_and_b32_e32 v54, 0xffff0000, v46
	v_lshlrev_b32_e32 v61, 16, v49
	v_lshlrev_b32_e32 v60, 16, v47
	v_and_b32_e32 v59, 0xffff0000, v49
	v_and_b32_e32 v58, 0xffff0000, v47
	s_waitcnt vmcnt(2)
	v_lshlrev_b32_e32 v47, 16, v95
	v_lshlrev_b32_e32 v46, 16, v94
	v_and_b32_e32 v49, 0xffff0000, v95
	v_and_b32_e32 v48, 0xffff0000, v94
	s_waitcnt vmcnt(1)
	v_lshlrev_b32_e32 v12, 16, v96
	v_and_b32_e32 v13, 0xffff0000, v96
	v_lshlrev_b32_e32 v14, 16, v97
	v_and_b32_e32 v15, 0xffff0000, v97
	v_lshlrev_b32_e32 v8, 16, v98
	v_and_b32_e32 v9, 0xffff0000, v98
	v_lshlrev_b32_e32 v10, 16, v99
	v_and_b32_e32 v11, 0xffff0000, v99
	s_waitcnt vmcnt(0)
	v_lshlrev_b32_e32 v4, 16, v100
	v_and_b32_e32 v5, 0xffff0000, v100
	v_lshlrev_b32_e32 v6, 16, v101
	v_and_b32_e32 v7, 0xffff0000, v101
	v_pk_fma_f32 v[94:95], v[104:105], v[104:105], v[120:121]
	v_pk_fma_f32 v[96:97], v[108:109], v[108:109], v[122:123]
	v_pk_fma_f32 v[98:99], v[112:113], v[112:113], v[124:125]
	v_pk_fma_f32 v[100:101], v[116:117], v[116:117], v[126:127]
	v_mul_f32_e32 v87, v68, v68
	v_mul_f32_e32 v140, v69, v69
	v_mul_f32_e32 v141, v70, v70
	v_mul_f32_e32 v142, v71, v71
	v_mul_f32_e32 v135, v65, v65
	v_mul_f32_e32 v137, v66, v66
	v_mul_f32_e32 v138, v67, v67
	v_lshlrev_b32_e32 v51, 16, v93
	v_lshlrev_b32_e32 v50, 16, v92
	v_and_b32_e32 v53, 0xffff0000, v93
	v_and_b32_e32 v52, 0xffff0000, v92
	v_lshlrev_b32_e32 v0, 16, v102
	v_and_b32_e32 v1, 0xffff0000, v102
	v_lshlrev_b32_e32 v2, 16, v103
	v_and_b32_e32 v3, 0xffff0000, v103
	v_mov_b32_e32 v92, v104
	v_mov_b32_e32 v93, v106
	v_mov_b32_e32 v106, v105
	v_pk_fma_f32 v[102:103], v[76:77], v[76:77], v[62:63] op_sel_hi:[1,1,0]
	v_pk_fma_f32 v[104:105], v[78:79], v[78:79], v[128:129] op_sel_hi:[1,1,0]
	v_pk_fma_f32 v[120:121], v[72:73], v[72:73], v[130:131] op_sel_hi:[1,1,0]
	v_pk_fma_f32 v[122:123], v[74:75], v[74:75], v[132:133] op_sel_hi:[1,1,0]
	v_pk_add_f32 v[94:95], v[94:95], v[94:95] op_sel:[0,1] op_sel_hi:[1,0]
	v_pk_add_f32 v[96:97], v[96:97], v[96:97] op_sel:[0,1] op_sel_hi:[1,0]
	v_pk_add_f32 v[98:99], v[98:99], v[98:99] op_sel:[0,1] op_sel_hi:[1,0]
	v_pk_add_f32 v[100:101], v[100:101], v[100:101] op_sel:[0,1] op_sel_hi:[1,0]
	v_mov_b32_e32 v103, v133
	v_mov_b32_e32 v105, v135
	v_mov_b32_e32 v121, v137
	v_mov_b32_e32 v123, v138
	v_mov_b32_e32 v95, v87
	v_mov_b32_e32 v97, v140
	v_mov_b32_e32 v99, v141
	v_mov_b32_e32 v101, v142
	v_pk_mul_f32 v[124:125], v[54:55], v[54:55]
	v_pk_mul_f32 v[126:127], v[58:59], v[58:59]
	v_pk_add_f32 v[102:103], v[102:103], v[104:105]
	v_pk_add_f32 v[104:105], v[120:121], v[122:123]
	v_pk_add_f32 v[94:95], v[94:95], v[96:97]
	v_pk_add_f32 v[96:97], v[98:99], v[100:101]
	v_pk_mul_f32 v[128:129], v[52:53], v[52:53]
	v_pk_mul_f32 v[130:131], v[48:49], v[48:49]
	v_pk_fma_f32 v[124:125], v[56:57], v[56:57], v[124:125]
	v_pk_fma_f32 v[126:127], v[60:61], v[60:61], v[126:127]
	v_pk_add_f32 v[98:99], v[102:103], v[104:105]
	v_pk_add_f32 v[94:95], v[94:95], v[96:97]
	v_mul_f32_e32 v62, v13, v13
	v_mul_f32_e32 v132, v15, v15
	v_mul_f32_e32 v134, v9, v9
	v_mul_f32_e32 v136, v11, v11
	v_pk_fma_f32 v[128:129], v[50:51], v[50:51], v[128:129]
	v_pk_fma_f32 v[130:131], v[46:47], v[46:47], v[130:131]
	v_pk_add_f32 v[120:121], v[124:125], v[126:127]
	v_pk_add_f32 v[94:95], v[94:95], v[98:99]
	v_mul_f32_e32 v143, v4, v4
	v_mul_f32_e32 v144, v5, v5
	v_mul_f32_e32 v145, v6, v6
	v_mul_f32_e32 v146, v7, v7
	v_mul_f32_e32 v147, v0, v0
	v_mul_f32_e32 v148, v1, v1
	v_mul_f32_e32 v149, v2, v2
	v_mul_f32_e32 v150, v3, v3
	v_pk_fma_f32 v[138:139], v[12:13], v[12:13], v[62:63] op_sel_hi:[1,1,0]
	v_pk_fma_f32 v[132:133], v[14:15], v[14:15], v[132:133] op_sel_hi:[1,1,0]
	v_pk_fma_f32 v[134:135], v[8:9], v[8:9], v[134:135] op_sel_hi:[1,1,0]
	v_pk_fma_f32 v[136:137], v[10:11], v[10:11], v[136:137] op_sel_hi:[1,1,0]
	v_pk_add_f32 v[122:123], v[128:129], v[128:129] op_sel:[0,1] op_sel_hi:[1,0]
	v_pk_add_f32 v[124:125], v[130:131], v[130:131] op_sel:[0,1] op_sel_hi:[1,0]
	v_pk_add_f32 v[100:101], v[120:121], v[120:121] op_sel:[0,1] op_sel_hi:[1,0]
	v_pk_add_f32 v[94:95], v[94:95], v[94:95] op_sel:[0,1] op_sel_hi:[1,0]
	v_mov_b32_e32 v139, v147
	v_mov_b32_e32 v133, v148
	v_mov_b32_e32 v135, v149
	v_mov_b32_e32 v137, v150
	v_mov_b32_e32 v123, v145
	v_mov_b32_e32 v125, v146
	v_mov_b32_e32 v101, v144
	v_mov_b32_e32 v95, v143
	v_pk_add_f32 v[102:103], v[138:139], v[132:133]
	v_pk_add_f32 v[104:105], v[134:135], v[136:137]
	v_pk_add_f32 v[96:97], v[122:123], v[124:125]
	v_pk_add_f32 v[94:95], v[94:95], v[100:101]
	v_pk_add_f32 v[102:103], v[102:103], v[104:105]
	v_pk_add_f32 v[94:95], v[94:95], v[96:97]
	s_nop 0
	v_pk_add_f32 v[94:95], v[94:95], v[102:103]
	s_nop 0
	v_add_f32_e32 v62, v94, v95
	ds_bpermute_b32 v87, v63, v62
	s_waitcnt lgkmcnt(0)
	v_add_f32_e32 v62, v62, v87
	ds_bpermute_b32 v87, v80, v62
	s_waitcnt lgkmcnt(0)
	v_add_f32_e32 v62, v62, v87
	ds_bpermute_b32 v87, v81, v62
	s_waitcnt lgkmcnt(0)
	v_add_f32_e32 v62, v62, v87
	ds_bpermute_b32 v87, v82, v62
	s_waitcnt lgkmcnt(0)
	v_add_f32_e32 v62, v62, v87
	ds_bpermute_b32 v87, v83, v62
	s_waitcnt lgkmcnt(0)
	v_add_f32_e32 v62, v62, v87
	ds_bpermute_b32 v87, v84, v62
	s_waitcnt lgkmcnt(0)
	v_add_f32_e32 v62, v62, v87
	v_fmamk_f32 v62, v62, 0x39800000, v85
	v_mul_f32_e32 v87, 0x4f800000, v62
	v_cmp_gt_f32_e32 vcc, s7, v62
	s_nop 1
	v_cndmask_b32_e32 v62, v62, v87, vcc
	v_sqrt_f32_e32 v87, v62
	s_nop 0
	v_add_u32_e32 v94, -1, v87
	v_add_u32_e32 v95, 1, v87
	v_fma_f32 v96, -v94, v87, v62
	v_fma_f32 v97, -v95, v87, v62
	v_cmp_ge_f32_e64 s[0:1], 0, v96
	s_nop 1
	v_cndmask_b32_e64 v87, v87, v94, s[0:1]
	v_cmp_lt_f32_e64 s[0:1], 0, v97
	s_nop 1
	v_cndmask_b32_e64 v87, v87, v95, s[0:1]
	v_mul_f32_e32 v94, 0x37800000, v87
	v_cndmask_b32_e32 v87, v87, v94, vcc
	v_cmp_class_f32_e32 vcc, v62, v86
	s_nop 1
	v_cndmask_b32_e32 v62, v87, v62, vcc
	v_div_scale_f32 v87, s[0:1], v62, v62, 1.0
	v_rcp_f32_e32 v95, v87
	v_div_scale_f32 v94, vcc, 1.0, v62, 1.0
	v_fma_f32 v96, -v87, v95, 1.0
	v_fmac_f32_e32 v95, v96, v95
	v_mul_f32_e32 v96, v94, v95
	v_fma_f32 v97, -v87, v96, v94
	v_fmac_f32_e32 v96, v97, v95
	v_fma_f32 v87, -v87, v96, v94
	v_div_fmas_f32 v87, v87, v95, v96
	v_div_fixup_f32 v62, v87, v62, 1.0
	v_pk_mul_f32 v[92:93], v[62:63], v[92:93] op_sel_hi:[0,1]
	v_pk_mul_f32 v[94:95], v[62:63], v[106:107] op_sel_hi:[0,1]
	v_pk_mul_f32 v[90:91], v[90:91], v[94:95]
	v_pk_mul_f32 v[88:89], v[88:89], v[92:93]
	global_store_dwordx4 v[42:43], v[88:91], off
	v_mov_b32_e32 v92, v109
	v_mov_b32_e32 v93, v111
	v_mov_b32_e32 v109, v110
	v_pk_mul_f32 v[92:93], v[62:63], v[92:93] op_sel_hi:[0,1]
	v_pk_mul_f32 v[94:95], v[62:63], v[108:109] op_sel_hi:[0,1]
	v_pk_mul_f32 v[78:79], v[62:63], v[78:79] op_sel_hi:[0,1]
	v_pk_mul_f32 v[76:77], v[62:63], v[76:77] op_sel_hi:[0,1]
	v_pk_mul_f32 v[74:75], v[62:63], v[74:75] op_sel_hi:[0,1]
	v_pk_mul_f32 v[72:73], v[62:63], v[72:73] op_sel_hi:[0,1]
	v_pk_mul_f32 v[70:71], v[62:63], v[70:71] op_sel_hi:[0,1]
	v_pk_mul_f32 v[68:69], v[62:63], v[68:69] op_sel_hi:[0,1]
	v_pk_mul_f32 v[66:67], v[62:63], v[66:67] op_sel_hi:[0,1]
	v_pk_mul_f32 v[64:65], v[62:63], v[64:65] op_sel_hi:[0,1]
	v_pk_mul_f32 v[14:15], v[62:63], v[14:15] op_sel_hi:[0,1]
	v_pk_mul_f32 v[12:13], v[62:63], v[12:13] op_sel_hi:[0,1]
	v_pk_mul_f32 v[10:11], v[62:63], v[10:11] op_sel_hi:[0,1]
	v_pk_mul_f32 v[8:9], v[62:63], v[8:9] op_sel_hi:[0,1]
	v_pk_mul_f32 v[6:7], v[62:63], v[6:7] op_sel_hi:[0,1]
	v_pk_mul_f32 v[4:5], v[62:63], v[4:5] op_sel_hi:[0,1]
	v_pk_mul_f32 v[2:3], v[62:63], v[2:3] op_sel_hi:[0,1]
	v_pk_mul_f32 v[0:1], v[62:63], v[0:1] op_sel_hi:[0,1]
	s_nop 0
	v_pk_mul_f32 v[88:89], v[152:153], v[94:95]
	v_pk_mul_f32 v[90:91], v[154:155], v[92:93]
	global_store_dwordx4 v[42:43], v[88:91], off offset:16
	v_mov_b32_e32 v92, v113
	v_mov_b32_e32 v93, v115
	v_mov_b32_e32 v113, v114
	v_pk_mul_f32 v[92:93], v[62:63], v[92:93] op_sel_hi:[0,1]
	v_pk_mul_f32 v[94:95], v[62:63], v[112:113] op_sel_hi:[0,1]
	s_nop 0
	v_pk_mul_f32 v[88:89], v[156:157], v[94:95]
	v_pk_mul_f32 v[90:91], v[158:159], v[92:93]
	global_store_dwordx4 v[42:43], v[88:91], off offset:2048
	v_mov_b32_e32 v92, v117
	v_mov_b32_e32 v93, v119
	v_mov_b32_e32 v117, v118
	v_pk_mul_f32 v[92:93], v[62:63], v[92:93] op_sel_hi:[0,1]
	v_pk_mul_f32 v[94:95], v[62:63], v[116:117] op_sel_hi:[0,1]
	s_nop 0
	v_pk_mul_f32 v[88:89], v[160:161], v[94:95]
	v_pk_mul_f32 v[90:91], v[162:163], v[92:93]
	global_store_dwordx4 v[42:43], v[88:91], off offset:2064
	v_add_co_u32_e32 v92, vcc, s8, v42
	s_nop 0
	v_pk_mul_f32 v[76:77], v[164:165], v[76:77]
	v_addc_co_u32_e32 v93, vcc, 0, v43, vcc
	v_pk_mul_f32 v[78:79], v[166:167], v[78:79]
	global_store_dwordx4 v[92:93], v[76:79], off offset:-4096
	v_add_co_u32_e32 v88, vcc, s6, v42
	s_nop 0
	v_pk_mul_f32 v[72:73], v[168:169], v[72:73]
	v_addc_co_u32_e32 v89, vcc, 0, v43, vcc
	v_pk_mul_f32 v[74:75], v[170:171], v[74:75]
	global_store_dwordx4 v[88:89], v[72:75], off offset:16
	s_nop 0
	v_pk_mul_f32 v[68:69], v[68:69], v[172:173]
	v_pk_mul_f32 v[70:71], v[70:71], v[174:175]
	global_store_dwordx4 v[88:89], v[68:71], off offset:2048
	s_nop 0
	v_pk_mul_f32 v[64:65], v[64:65], v[176:177]
	v_pk_mul_f32 v[66:67], v[66:67], v[178:179]
	global_store_dwordx4 v[88:89], v[64:67], off offset:2064
	v_mov_b32_e32 v68, v60
	v_mov_b32_e32 v69, v58
	v_mov_b32_e32 v70, v56
	v_mov_b32_e32 v71, v54
	v_pk_mul_f32 v[68:69], v[62:63], v[68:69] op_sel_hi:[0,1]
	v_pk_mul_f32 v[70:71], v[62:63], v[70:71] op_sel_hi:[0,1]
	v_mov_b32_e32 v58, v61
	v_mov_b32_e32 v54, v57
	v_pk_mul_f32 v[56:57], v[62:63], v[58:59] op_sel_hi:[0,1]
	v_pk_mul_f32 v[54:55], v[62:63], v[54:55] op_sel_hi:[0,1]
	v_mov_b32_e32 v58, v51
	v_mov_b32_e32 v59, v53
	v_mov_b32_e32 v51, v52
	v_pk_mul_f32 v[52:53], v[62:63], v[58:59] op_sel_hi:[0,1]
	v_pk_mul_f32 v[50:51], v[62:63], v[50:51] op_sel_hi:[0,1]
	s_nop 0
	v_pk_mul_f32 v[64:65], v[70:71], v[180:181]
	v_pk_mul_f32 v[66:67], v[68:69], v[182:183]
	global_store_dwordx4 v[92:93], v[64:67], off
	s_nop 0
	v_pk_mul_f32 v[54:55], v[54:55], v[184:185]
	v_pk_mul_f32 v[56:57], v[56:57], v[186:187]
	global_store_dwordx4 v[92:93], v[54:57], off offset:16
	s_nop 0
	v_pk_mul_f32 v[50:51], v[50:51], v[188:189]
	v_pk_mul_f32 v[52:53], v[52:53], v[190:191]
	global_store_dwordx4 v[92:93], v[50:53], off offset:2048
	v_mov_b32_e32 v54, v47
	v_mov_b32_e32 v55, v49
	v_mov_b32_e32 v47, v48
	v_pk_mul_f32 v[48:49], v[62:63], v[54:55] op_sel_hi:[0,1]
	v_pk_mul_f32 v[46:47], v[62:63], v[46:47] op_sel_hi:[0,1]
	s_nop 0
	v_pk_mul_f32 v[46:47], v[46:47], v[192:193]
	v_pk_mul_f32 v[48:49], v[48:49], v[194:195]
	global_store_dwordx4 v[92:93], v[46:49], off offset:2064
	v_add_co_u32_e32 v50, vcc, s9, v42
	s_nop 0
	v_pk_mul_f32 v[12:13], v[12:13], v[196:197]
	v_addc_co_u32_e32 v51, vcc, 0, v43, vcc
	v_pk_mul_f32 v[14:15], v[14:15], v[198:199]
	global_store_dwordx4 v[50:51], v[12:15], off
	v_lshl_add_u64 v[42:43], v[42:43], 0, s[2:3]
	s_nop 0
	v_pk_mul_f32 v[8:9], v[8:9], v[200:201]
	v_pk_mul_f32 v[10:11], v[10:11], v[202:203]
	global_store_dwordx4 v[50:51], v[8:11], off offset:16
	s_nop 0
	v_pk_mul_f32 v[4:5], v[4:5], v[204:205]
	v_pk_mul_f32 v[6:7], v[6:7], v[206:207]
	global_store_dwordx4 v[50:51], v[4:7], off offset:2048
	s_nop 0
	v_pk_mul_f32 v[0:1], v[0:1], v[208:209]
	v_pk_mul_f32 v[2:3], v[2:3], v[210:211]
	global_store_dwordx4 v[50:51], v[0:3], off offset:2064
	s_cbranch_scc1 .LBB0_1450
